# v30: v27 + accumulator zero-init before each GEMM K-loop with 64 v_mov_b64 instead of 128 v_mov_b32
# speedup vs baseline: 1.0083x; 1.0005x over previous
.LBB0_229:
	s_ashr_i32 s57, s56, 31
	s_lshl_b64 s[30:31], s[56:57], 21
	s_add_u32 s24, s36, s30
	v_readlane_b32 s20, v254, 7
	s_addc_u32 s25, s20, s31
	s_and_b64 s[30:31], s[88:89], exec
	s_cselect_b32 s34, s25, s1
	s_cselect_b32 s35, s24, s0
	s_ashr_i32 s27, s26, 31
	s_lshl_b64 s[30:31], s[26:27], 21
	v_readlane_b32 s20, v254, 2
	s_add_u32 s20, s20, s30
	v_readlane_b32 s21, v254, 3
	s_addc_u32 s21, s21, s31
	s_and_b64 s[30:31], s[88:89], exec
	s_cselect_b32 s27, s21, s29
	s_cselect_b32 s40, s20, s28
	s_add_u32 s0, s0, 0x100080
	s_addc_u32 s1, s1, 0
	s_add_u32 s41, s28, 0x100
	v_mov_b64_e32 v[2:3], 0
	v_mov_b64_e32 v[4:5], 0
	v_mov_b64_e32 v[6:7], 0
	v_mov_b64_e32 v[8:9], 0
	v_mov_b64_e32 v[10:11], 0
	v_mov_b64_e32 v[12:13], 0
	v_mov_b64_e32 v[14:15], 0
	v_mov_b64_e32 v[16:17], 0
	v_mov_b64_e32 v[18:19], 0
	v_mov_b64_e32 v[20:21], 0
	v_mov_b64_e32 v[22:23], 0
	v_mov_b64_e32 v[24:25], 0
	v_mov_b64_e32 v[26:27], 0
	v_mov_b64_e32 v[28:29], 0
	v_mov_b64_e32 v[30:31], 0
	v_mov_b64_e32 v[32:33], 0
	v_mov_b64_e32 v[34:35], 0
	v_mov_b64_e32 v[36:37], 0
	v_mov_b64_e32 v[38:39], 0
	v_mov_b64_e32 v[40:41], 0
	v_mov_b64_e32 v[42:43], 0
	v_mov_b64_e32 v[44:45], 0
	v_mov_b64_e32 v[46:47], 0
	v_mov_b64_e32 v[48:49], 0
	v_mov_b64_e32 v[50:51], 0
	v_mov_b64_e32 v[52:53], 0
	v_mov_b64_e32 v[54:55], 0
	v_mov_b64_e32 v[56:57], 0
	v_mov_b64_e32 v[58:59], 0
	v_mov_b64_e32 v[60:61], 0
	v_mov_b64_e32 v[62:63], 0
	v_mov_b64_e32 v[64:65], 0
	v_mov_b64_e32 v[66:67], 0
	v_mov_b64_e32 v[68:69], 0
	v_mov_b64_e32 v[70:71], 0
	v_mov_b64_e32 v[72:73], 0
	v_mov_b64_e32 v[74:75], 0
	v_mov_b64_e32 v[76:77], 0
	v_mov_b64_e32 v[78:79], 0
	v_mov_b64_e32 v[80:81], 0
	v_mov_b64_e32 v[82:83], 0
	v_mov_b64_e32 v[84:85], 0
	v_mov_b64_e32 v[86:87], 0
	v_mov_b64_e32 v[88:89], 0
	v_mov_b64_e32 v[90:91], 0
	v_mov_b64_e32 v[92:93], 0
	v_mov_b64_e32 v[94:95], 0
	v_mov_b64_e32 v[96:97], 0
	v_mov_b64_e32 v[98:99], 0
	v_mov_b64_e32 v[100:101], 0
	v_mov_b64_e32 v[102:103], 0
	v_mov_b64_e32 v[104:105], 0
	v_mov_b64_e32 v[106:107], 0
	v_mov_b64_e32 v[108:109], 0
	v_mov_b64_e32 v[110:111], 0
	v_mov_b64_e32 v[112:113], 0
	v_mov_b64_e32 v[114:115], 0
	v_mov_b64_e32 v[116:117], 0
	v_mov_b64_e32 v[118:119], 0
	v_mov_b64_e32 v[120:121], 0
	v_mov_b64_e32 v[122:123], 0
	v_mov_b64_e32 v[124:125], 0
	v_mov_b64_e32 v[126:127], 0
	v_mov_b64_e32 v[128:129], 0
	s_addc_u32 s43, s29, 0
	s_mov_b32 s50, -2

.LBB0_299:
	s_ashr_i32 s49, s48, 31
	s_lshl_b64 s[18:19], s[48:49], 20
	s_add_u32 s22, s92, s18
	v_readlane_b32 s18, v251, 32
	s_addc_u32 s23, s18, s19
	s_and_b64 s[18:19], s[38:39], exec
	s_cselect_b32 s18, s23, s1
	s_cselect_b32 s19, s22, s0
	s_ashr_i32 s27, s26, 31
	s_lshl_b64 s[24:25], s[26:27], 20
	s_add_u32 s24, s80, s24
	s_addc_u32 s25, s33, s25
	s_and_b64 s[30:31], s[38:39], exec
	s_cselect_b32 s27, s25, s29
	s_cselect_b32 s34, s24, s28
	s_add_u32 s0, s0, 0x80080
	s_addc_u32 s1, s1, 0
	s_add_u32 s35, s28, 0x100
	v_mov_b64_e32 v[18:19], 0
	v_mov_b64_e32 v[20:21], 0
	v_mov_b64_e32 v[22:23], 0
	v_mov_b64_e32 v[24:25], 0
	v_mov_b64_e32 v[26:27], 0
	v_mov_b64_e32 v[28:29], 0
	v_mov_b64_e32 v[30:31], 0
	v_mov_b64_e32 v[32:33], 0
	v_mov_b64_e32 v[34:35], 0
	v_mov_b64_e32 v[36:37], 0
	v_mov_b64_e32 v[38:39], 0
	v_mov_b64_e32 v[40:41], 0
	v_mov_b64_e32 v[42:43], 0
	v_mov_b64_e32 v[44:45], 0
	v_mov_b64_e32 v[46:47], 0
	v_mov_b64_e32 v[48:49], 0
	v_mov_b64_e32 v[50:51], 0
	v_mov_b64_e32 v[52:53], 0
	v_mov_b64_e32 v[54:55], 0
	v_mov_b64_e32 v[56:57], 0
	v_mov_b64_e32 v[58:59], 0
	v_mov_b64_e32 v[60:61], 0
	v_mov_b64_e32 v[62:63], 0
	v_mov_b64_e32 v[64:65], 0
	v_mov_b64_e32 v[66:67], 0
	v_mov_b64_e32 v[68:69], 0
	v_mov_b64_e32 v[70:71], 0
	v_mov_b64_e32 v[72:73], 0
	v_mov_b64_e32 v[74:75], 0
	v_mov_b64_e32 v[76:77], 0
	v_mov_b64_e32 v[78:79], 0
	v_mov_b64_e32 v[80:81], 0
	v_mov_b64_e32 v[82:83], 0
	v_mov_b64_e32 v[84:85], 0
	v_mov_b64_e32 v[86:87], 0
	v_mov_b64_e32 v[88:89], 0
	v_mov_b64_e32 v[90:91], 0
	v_mov_b64_e32 v[92:93], 0
	v_mov_b64_e32 v[94:95], 0
	v_mov_b64_e32 v[96:97], 0
	v_mov_b64_e32 v[98:99], 0
	v_mov_b64_e32 v[100:101], 0
	v_mov_b64_e32 v[102:103], 0
	v_mov_b64_e32 v[104:105], 0
	v_mov_b64_e32 v[106:107], 0
	v_mov_b64_e32 v[108:109], 0
	v_mov_b64_e32 v[110:111], 0
	v_mov_b64_e32 v[112:113], 0
	v_mov_b64_e32 v[114:115], 0
	v_mov_b64_e32 v[116:117], 0
	v_mov_b64_e32 v[118:119], 0
	v_mov_b64_e32 v[120:121], 0
	v_mov_b64_e32 v[122:123], 0
	v_mov_b64_e32 v[124:125], 0
	v_mov_b64_e32 v[126:127], 0
	v_mov_b64_e32 v[128:129], 0
	v_mov_b64_e32 v[130:131], 0
	v_mov_b64_e32 v[132:133], 0
	v_mov_b64_e32 v[134:135], 0
	v_mov_b64_e32 v[136:137], 0
	v_mov_b64_e32 v[138:139], 0
	v_mov_b64_e32 v[140:141], 0
	v_mov_b64_e32 v[142:143], 0
	v_mov_b64_e32 v[144:145], 0
	s_addc_u32 s40, s29, 0
	s_mov_b32 s41, -2

.LBB0_778:
	s_ashr_i32 s25, s24, 31
	s_lshl_b64 s[26:27], s[24:25], 20
	v_readlane_b32 s23, v253, 40
	s_add_u32 s26, s23, s26
	v_readlane_b32 s23, v253, 41
	s_addc_u32 s27, s23, s27
	s_and_b64 s[28:29], s[40:41], exec
	s_cselect_b32 s25, s27, s31
	s_cselect_b32 s53, s26, s30
	s_ashr_i32 s23, s22, 31
	s_lshl_b64 s[28:29], s[22:23], 20
	v_readlane_b32 s23, v253, 34
	s_add_u32 s28, s23, s28
	v_readlane_b32 s23, v253, 35
	s_addc_u32 s29, s23, s29
	s_and_b64 s[42:43], s[40:41], exec
	s_cselect_b32 s23, s29, s35
	s_cselect_b32 s54, s28, s34
	s_add_u32 s30, s30, 0x80080
	s_addc_u32 s31, s31, 0
	s_add_u32 s55, s34, 0x100
	v_mov_b64_e32 v[2:3], 0
	v_mov_b64_e32 v[4:5], 0
	v_mov_b64_e32 v[6:7], 0
	v_mov_b64_e32 v[8:9], 0
	v_mov_b64_e32 v[10:11], 0
	v_mov_b64_e32 v[12:13], 0
	v_mov_b64_e32 v[14:15], 0
	v_mov_b64_e32 v[16:17], 0
	v_mov_b64_e32 v[18:19], 0
	v_mov_b64_e32 v[20:21], 0
	v_mov_b64_e32 v[22:23], 0
	v_mov_b64_e32 v[24:25], 0
	v_mov_b64_e32 v[26:27], 0
	v_mov_b64_e32 v[28:29], 0
	v_mov_b64_e32 v[30:31], 0
	v_mov_b64_e32 v[32:33], 0
	v_mov_b64_e32 v[34:35], 0
	v_mov_b64_e32 v[36:37], 0
	v_mov_b64_e32 v[38:39], 0
	v_mov_b64_e32 v[40:41], 0
	v_mov_b64_e32 v[42:43], 0
	v_mov_b64_e32 v[44:45], 0
	v_mov_b64_e32 v[46:47], 0
	v_mov_b64_e32 v[48:49], 0
	v_mov_b64_e32 v[50:51], 0
	v_mov_b64_e32 v[52:53], 0
	v_mov_b64_e32 v[54:55], 0
	v_mov_b64_e32 v[56:57], 0
	v_mov_b64_e32 v[58:59], 0
	v_mov_b64_e32 v[60:61], 0
	v_mov_b64_e32 v[62:63], 0
	v_mov_b64_e32 v[64:65], 0
	v_mov_b64_e32 v[66:67], 0
	v_mov_b64_e32 v[68:69], 0
	v_mov_b64_e32 v[70:71], 0
	v_mov_b64_e32 v[72:73], 0
	v_mov_b64_e32 v[74:75], 0
	v_mov_b64_e32 v[76:77], 0
	v_mov_b64_e32 v[78:79], 0
	v_mov_b64_e32 v[80:81], 0
	v_mov_b64_e32 v[82:83], 0
	v_mov_b64_e32 v[84:85], 0
	v_mov_b64_e32 v[86:87], 0
	v_mov_b64_e32 v[88:89], 0
	v_mov_b64_e32 v[98:99], 0
	v_mov_b64_e32 v[100:101], 0
	v_mov_b64_e32 v[102:103], 0
	v_mov_b64_e32 v[104:105], 0
	v_mov_b64_e32 v[110:111], 0
	v_mov_b64_e32 v[112:113], 0
	v_mov_b64_e32 v[118:119], 0
	v_mov_b64_e32 v[120:121], 0
	v_mov_b64_e32 v[122:123], 0
	v_mov_b64_e32 v[124:125], 0
	v_mov_b64_e32 v[126:127], 0
	v_mov_b64_e32 v[128:129], 0
	v_mov_b64_e32 v[130:131], 0
	v_mov_b64_e32 v[132:133], 0
	v_mov_b64_e32 v[134:135], 0
	v_mov_b64_e32 v[136:137], 0
	v_mov_b64_e32 v[138:139], 0
	v_mov_b64_e32 v[140:141], 0
	v_mov_b64_e32 v[142:143], 0
	v_mov_b64_e32 v[144:145], 0
	s_addc_u32 s56, s35, 0
	s_mov_b32 s57, -2

.LBB0_800:
	s_ashr_i32 s25, s24, 31
	s_lshl_b64 s[26:27], s[24:25], 21
	s_add_u32 s26, s70, s26
	s_addc_u32 s27, s71, s27
	s_and_b64 s[28:29], s[38:39], exec
	s_cselect_b32 s25, s27, s31
	s_cselect_b32 s49, s26, s30
	s_ashr_i32 s23, s22, 31
	s_lshl_b64 s[28:29], s[22:23], 21
	v_readlane_b32 s23, v253, 52
	s_add_u32 s28, s23, s28
	v_readlane_b32 s23, v253, 53
	s_addc_u32 s29, s23, s29
	s_and_b64 s[40:41], s[38:39], exec
	s_cselect_b32 s23, s29, s35
	s_cselect_b32 s50, s28, s34
	s_add_u32 s30, s30, 0x100080
	s_addc_u32 s31, s31, 0
	s_add_u32 s51, s34, 0x100
	v_mov_b64_e32 v[2:3], 0
	v_mov_b64_e32 v[4:5], 0
	v_mov_b64_e32 v[6:7], 0
	v_mov_b64_e32 v[8:9], 0
	v_mov_b64_e32 v[10:11], 0
	v_mov_b64_e32 v[12:13], 0
	v_mov_b64_e32 v[14:15], 0
	v_mov_b64_e32 v[16:17], 0
	v_mov_b64_e32 v[18:19], 0
	v_mov_b64_e32 v[20:21], 0
	v_mov_b64_e32 v[22:23], 0
	v_mov_b64_e32 v[24:25], 0
	v_mov_b64_e32 v[26:27], 0
	v_mov_b64_e32 v[28:29], 0
	v_mov_b64_e32 v[30:31], 0
	v_mov_b64_e32 v[32:33], 0
	v_mov_b64_e32 v[34:35], 0
	v_mov_b64_e32 v[36:37], 0
	v_mov_b64_e32 v[38:39], 0
	v_mov_b64_e32 v[40:41], 0
	v_mov_b64_e32 v[42:43], 0
	v_mov_b64_e32 v[44:45], 0
	v_mov_b64_e32 v[46:47], 0
	v_mov_b64_e32 v[48:49], 0
	v_mov_b64_e32 v[50:51], 0
	v_mov_b64_e32 v[52:53], 0
	v_mov_b64_e32 v[54:55], 0
	v_mov_b64_e32 v[56:57], 0
	v_mov_b64_e32 v[58:59], 0
	v_mov_b64_e32 v[60:61], 0
	v_mov_b64_e32 v[62:63], 0
	v_mov_b64_e32 v[64:65], 0
	v_mov_b64_e32 v[66:67], 0
	v_mov_b64_e32 v[68:69], 0
	v_mov_b64_e32 v[70:71], 0
	v_mov_b64_e32 v[72:73], 0
	v_mov_b64_e32 v[74:75], 0
	v_mov_b64_e32 v[76:77], 0
	v_mov_b64_e32 v[78:79], 0
	v_mov_b64_e32 v[80:81], 0
	v_mov_b64_e32 v[82:83], 0
	v_mov_b64_e32 v[84:85], 0
	v_mov_b64_e32 v[86:87], 0
	v_mov_b64_e32 v[88:89], 0
	v_mov_b64_e32 v[90:91], 0
	v_mov_b64_e32 v[92:93], 0
	v_mov_b64_e32 v[94:95], 0
	v_mov_b64_e32 v[96:97], 0
	v_mov_b64_e32 v[98:99], 0
	v_mov_b64_e32 v[100:101], 0
	v_mov_b64_e32 v[102:103], 0
	v_mov_b64_e32 v[104:105], 0
	v_mov_b64_e32 v[106:107], 0
	v_mov_b64_e32 v[108:109], 0
	v_mov_b64_e32 v[110:111], 0
	v_mov_b64_e32 v[112:113], 0
	v_mov_b64_e32 v[114:115], 0
	v_mov_b64_e32 v[116:117], 0
	v_mov_b64_e32 v[118:119], 0
	v_mov_b64_e32 v[120:121], 0
	v_mov_b64_e32 v[122:123], 0
	v_mov_b64_e32 v[124:125], 0
	v_mov_b64_e32 v[126:127], 0
	v_mov_b64_e32 v[128:129], 0
	s_addc_u32 s52, s35, 0
	s_mov_b32 s53, -2
